# v57 + retention chain GEMM: per-unit epilogue alignment barriers dropped (epilogues stay staggered like the EpiBf16 phases), final compensation barrier kept
# speedup vs baseline: 1.0049x; 1.0049x over previous
; #define PG8_BAR __builtin_amdgcn_s_barrier()
; template <class Epi, class Sched, bool ALIGN_EPI, bool SP2>
; __device__ __forceinline__ void gemm_phase(LAS unsigned char* lds, const int tid, const Gemm g, const Sched& S, const Epi& E) {
;     ...
;         if constexpr (ALIGN_EPI) { if (wr == 0) PG8_BAR; }
;         if constexpr (Epi::FUSED_LAST) { if (has_next) E(acc, cur, wr, wc, fr, fq); }
;         else E(acc, cur, wr, wc, fr, fq);
;         if (!has_next) break;
;         bool rst = true; if constexpr (Epi::KEEPS) rst = E.reset(cur);
;         if (rst) {
; #pragma unroll
;         for (int a = 0; a < 2; ++a)
; #pragma unroll
;             for (int b = 0; b < 2; ++b)
; #pragma unroll
;                 for (int m = 0; m < 4; ++m)
; #pragma unroll
;                     for (int n = 0; n < 2; ++n) acc[a][b][m][n] = (f32x4){0.f, 0.f, 0.f, 0.f};
;         }
;         cur = nxt; cA = nA; cB = nB; ++ui;
;         if constexpr (ALIGN_EPI) { if (wr == 1) PG8_BAR; }
.LBB0_740:
.LBB0_741:
	s_mov_b64 s[18:19], 0

; #define PG8_STAGE(bufoff, gbase, voff) do { _Pragma("unroll") for (int _i = 0; _i < 2; ++_i) \
;         __builtin_amdgcn_global_load_lds((const GAS unsigned*)((const GAS char*)(gbase) + (voff)[_i]), (LAS unsigned*)(lds + (bufoff) + ldsw + _i * 8192), 16, 0, 0); } while (0)
; #define PG8_LDA(dst, b, h) do { _Pragma("unroll") for (int m = 0; m < 4; ++m) _Pragma("unroll") for (int k = 0; k < 2; ++k) dst[m][k] = *(const LAS bf16x8*)(lds + PG8_SA(b, h) + aoff + m * 2048 + k * 1024); } while (0)
; #define PG8_LDB(dst, b, h) do { _Pragma("unroll") for (int n = 0; n < 2; ++n) _Pragma("unroll") for (int k = 0; k < 2; ++k) dst[n][k] = *(const LAS bf16x8*)(lds + PG8_SB(b, h) + boff + n * 2048 + k * 1024); } while (0)
; #define PG8_MMA(ai, bj, At, Bt) do { __builtin_amdgcn_sched_barrier(0); _Pragma("unroll") for (int m = 0; m < 4; ++m) _Pragma("unroll") for (int n = 0; n < 2; ++n) _Pragma("unroll") for (int k = 0; k < 2; ++k) \
;         acc[ai][bj][m][n] = __builtin_amdgcn_mfma_f32_16x16x32_bf16(Bt[n][k], At[m][k], acc[ai][bj][m][n], 0, 0, 0); __builtin_amdgcn_sched_barrier(0); } while (0)
; #define PG8_WAIT_V(n) asm volatile("s_waitcnt vmcnt(" #n ")" ::: "memory")
; #define PG8_WAIT_L(n) asm volatile("s_waitcnt lgkmcnt(" #n ")" ::: "memory")
; #define PG8_BAR __builtin_amdgcn_s_barrier()
; #define PG8_SCHED __builtin_amdgcn_sched_barrier(0)
; template <class Epi, class Sched, bool ALIGN_EPI, bool SP2>
; __device__ __forceinline__ void gemm_phase(LAS unsigned char* lds, const int tid, const Gemm g, const Sched& S, const Epi& E) {
;     ...
;             PG8_LDB(B0, 0, 0); PG8_LDB(B1, 0, 1); PG8_SCHED; PG8_LDA(At, 0, 0); PG8_STAGE(PG8_SA(1, 1), a1 + hstepA, voffA);
;             PG8_WAIT_V(8); PG8_WAIT_L(0); PG8_BAR; PG8_MMA(0, 0, At, B0); PG8_MMA(0, 1, At, B1); PG8_BAR; PG8_SCHED;
;             PG8_LDA(At, 0, 1); PG8_STAGE(PG8_SB(0, 0), b2, voffB); PG8_STAGE(PG8_SB(0, 1), b2 + hstepB, voffB); PG8_STAGE(PG8_SA(0, 0), a2, voffA);
;             PG8_WAIT_V(8); PG8_WAIT_L(0); PG8_BAR; PG8_MMA(1, 0, At, B0); PG8_MMA(1, 1, At, B1); PG8_BAR; PG8_SCHED;
.Lch_rj2:
	s_mov_b32 s100, 0
	s_waitcnt lgkmcnt(0)
	s_barrier
	s_waitcnt lgkmcnt(0)
	v_mfma_f32_16x16x32_bf16 v[62:65], v[142:145], v[174:177], v[62:65]
	v_mfma_f32_16x16x32_bf16 v[58:61], v[150:153], v[174:177], v[58:61]
	v_mfma_f32_16x16x32_bf16 v[54:57], v[142:145], v[182:185], v[54:57]
	v_mfma_f32_16x16x32_bf16 v[50:53], v[150:153], v[182:185], v[50:53]
	v_mfma_f32_16x16x32_bf16 v[46:49], v[142:145], v[190:193], v[46:49]
	v_mfma_f32_16x16x32_bf16 v[42:45], v[150:153], v[190:193], v[42:45]
	v_mfma_f32_16x16x32_bf16 v[38:41], v[142:145], v[198:201], v[38:41]
	v_mfma_f32_16x16x32_bf16 v[34:37], v[150:153], v[198:201], v[34:37]
	v_mfma_f32_16x16x32_bf16 v[62:65], v[146:149], v[178:181], v[62:65]
	v_mfma_f32_16x16x32_bf16 v[58:61], v[154:157], v[178:181], v[58:61]
	v_mfma_f32_16x16x32_bf16 v[54:57], v[146:149], v[186:189], v[54:57]
	v_mfma_f32_16x16x32_bf16 v[50:53], v[154:157], v[186:189], v[50:53]
	v_mfma_f32_16x16x32_bf16 v[46:49], v[146:149], v[194:197], v[46:49]
	v_mfma_f32_16x16x32_bf16 v[42:45], v[154:157], v[194:197], v[42:45]
	v_mfma_f32_16x16x32_bf16 v[38:41], v[146:149], v[214:217], v[38:41]
	v_mfma_f32_16x16x32_bf16 v[34:37], v[154:157], v[214:217], v[34:37]
	v_mfma_f32_16x16x32_bf16 v[30:33], v[158:161], v[174:177], v[30:33]
	v_mfma_f32_16x16x32_bf16 v[26:29], v[166:169], v[174:177], v[26:29]
	v_mfma_f32_16x16x32_bf16 v[22:25], v[158:161], v[182:185], v[22:25]
	v_mfma_f32_16x16x32_bf16 v[18:21], v[166:169], v[182:185], v[18:21]
	v_mfma_f32_16x16x32_bf16 v[14:17], v[158:161], v[190:193], v[14:17]
	v_mfma_f32_16x16x32_bf16 v[10:13], v[166:169], v[190:193], v[10:13]
	v_mfma_f32_16x16x32_bf16 v[6:9], v[158:161], v[198:201], v[6:9]
	v_mfma_f32_16x16x32_bf16 v[2:5], v[166:169], v[198:201], v[2:5]
	v_mfma_f32_16x16x32_bf16 v[30:33], v[162:165], v[178:181], v[30:33]
	v_mfma_f32_16x16x32_bf16 v[26:29], v[170:173], v[178:181], v[26:29]
	v_mfma_f32_16x16x32_bf16 v[22:25], v[162:165], v[186:189], v[22:25]
	v_mfma_f32_16x16x32_bf16 v[18:21], v[170:173], v[186:189], v[18:21]
	v_mfma_f32_16x16x32_bf16 v[14:17], v[162:165], v[194:197], v[14:17]
	v_mfma_f32_16x16x32_bf16 v[10:13], v[170:173], v[194:197], v[10:13]
	v_mfma_f32_16x16x32_bf16 v[6:9], v[162:165], v[214:217], v[6:9]
	v_mfma_f32_16x16x32_bf16 v[2:5], v[170:173], v[214:217], v[2:5]
	s_barrier
	v_add_u32_e32 v136, s82, v1
	ds_read_b128 v[142:145], v136
	ds_read_b128 v[146:149], v136 offset:1024
	ds_read_b128 v[150:153], v136 offset:2048
	ds_read_b128 v[154:157], v136 offset:3072
	v_add_u32_e32 v136, s73, v1
	ds_read_b128 v[158:161], v136
	ds_read_b128 v[162:165], v136 offset:1024
	ds_read_b128 v[166:169], v136 offset:2048
	ds_read_b128 v[170:173], v136 offset:3072
	s_mov_b32 m0, s61
	v_lshl_add_u64 v[224:225], s[34:35], 0, v[130:131]
	ds_read_b128 v[174:177], v140 offset:32768
	ds_read_b128 v[178:181], v140 offset:33792
	ds_read_b128 v[182:185], v140 offset:34816
	ds_read_b128 v[186:189], v140 offset:35840
	ds_read_b128 v[190:193], v140 offset:36864
	ds_read_b128 v[194:197], v140 offset:37888
	ds_read_b128 v[198:201], v140 offset:38912
	ds_read_b128 v[214:217], v140 offset:39936
	global_load_lds_dwordx4 v[224:225], off
	v_lshl_add_u64 v[224:225], s[34:35], 0, v[132:133]
	s_mov_b32 m0, s62
	s_nop 0
	global_load_lds_dwordx4 v[224:225], off
	s_waitcnt vmcnt(8)
	s_waitcnt lgkmcnt(0)
	s_barrier
	s_waitcnt lgkmcnt(0)
	v_mfma_f32_16x16x32_bf16 v[126:129], v[142:145], v[174:177], v[126:129]
	v_mfma_f32_16x16x32_bf16 v[122:125], v[150:153], v[174:177], v[122:125]
	v_mfma_f32_16x16x32_bf16 v[118:121], v[142:145], v[182:185], v[118:121]
	v_mfma_f32_16x16x32_bf16 v[114:117], v[150:153], v[182:185], v[114:117]
	v_mfma_f32_16x16x32_bf16 v[110:113], v[142:145], v[190:193], v[110:113]
	v_mfma_f32_16x16x32_bf16 v[106:109], v[150:153], v[190:193], v[106:109]
	v_mfma_f32_16x16x32_bf16 v[102:105], v[142:145], v[198:201], v[102:105]
	v_mfma_f32_16x16x32_bf16 v[98:101], v[150:153], v[198:201], v[98:101]
	v_mfma_f32_16x16x32_bf16 v[126:129], v[146:149], v[178:181], v[126:129]
	v_mfma_f32_16x16x32_bf16 v[122:125], v[154:157], v[178:181], v[122:125]
	v_mfma_f32_16x16x32_bf16 v[118:121], v[146:149], v[186:189], v[118:121]
	v_mfma_f32_16x16x32_bf16 v[114:117], v[154:157], v[186:189], v[114:117]
	v_mfma_f32_16x16x32_bf16 v[110:113], v[146:149], v[194:197], v[110:113]
	v_mfma_f32_16x16x32_bf16 v[106:109], v[154:157], v[194:197], v[106:109]
	v_mfma_f32_16x16x32_bf16 v[102:105], v[146:149], v[214:217], v[102:105]
	v_mfma_f32_16x16x32_bf16 v[98:101], v[154:157], v[214:217], v[98:101]
	v_mfma_f32_16x16x32_bf16 v[94:97], v[158:161], v[174:177], v[94:97]
	v_mfma_f32_16x16x32_bf16 v[90:93], v[166:169], v[174:177], v[90:93]
	v_mfma_f32_16x16x32_bf16 v[86:89], v[158:161], v[182:185], v[86:89]
	v_mfma_f32_16x16x32_bf16 v[82:85], v[166:169], v[182:185], v[82:85]
	v_mfma_f32_16x16x32_bf16 v[78:81], v[158:161], v[190:193], v[78:81]
	v_mfma_f32_16x16x32_bf16 v[74:77], v[166:169], v[190:193], v[74:77]
	v_mfma_f32_16x16x32_bf16 v[70:73], v[158:161], v[198:201], v[70:73]
	v_mfma_f32_16x16x32_bf16 v[66:69], v[166:169], v[198:201], v[66:69]
	v_mfma_f32_16x16x32_bf16 v[94:97], v[162:165], v[178:181], v[94:97]
	v_mfma_f32_16x16x32_bf16 v[90:93], v[170:173], v[178:181], v[90:93]
	v_mfma_f32_16x16x32_bf16 v[86:89], v[162:165], v[186:189], v[86:89]
	v_mfma_f32_16x16x32_bf16 v[82:85], v[170:173], v[186:189], v[82:85]
	v_mfma_f32_16x16x32_bf16 v[78:81], v[162:165], v[194:197], v[78:81]
	v_mfma_f32_16x16x32_bf16 v[74:77], v[170:173], v[194:197], v[74:77]
	v_mfma_f32_16x16x32_bf16 v[70:73], v[162:165], v[214:217], v[70:73]
	v_mfma_f32_16x16x32_bf16 v[66:69], v[170:173], v[214:217], v[66:69]
	s_barrier
; #define PG8_WAIT_V(n) asm volatile("s_waitcnt vmcnt(" #n ")" ::: "memory")
; #define PG8_WAIT_L(n) asm volatile("s_waitcnt lgkmcnt(" #n ")" ::: "memory")
; template <class Epi, class Sched, bool ALIGN_EPI, bool SP2>
; __device__ __forceinline__ void gemm_phase(LAS unsigned char* lds, const int tid, const Gemm g, const Sched& S, const Epi& E) {
;     ...
;             PG8_LDB(B0, 1, 0); PG8_LDB(B1, 1, 1); PG8_SCHED; PG8_LDA(At, 1, 0); PG8_STAGE(PG8_SA(0, 1), a2 + hstepA, voffA);
;             PG8_WAIT_V(8); PG8_WAIT_L(0); PG8_BAR; PG8_MMA(0, 0, At, B0); PG8_MMA(0, 1, At, B1); PG8_BAR; PG8_SCHED;
;             PG8_LDA(At, 1, 1); PG8_STAGE(PG8_SB(1, 0), b3, voffB); PG8_STAGE(PG8_SB(1, 1), b3 + hstepB, voffB); PG8_STAGE(PG8_SA(1, 0), a3, voffA);
;             PG8_WAIT_V(8); PG8_WAIT_L(0); PG8_BAR; PG8_MMA(1, 0, At, B0); PG8_MMA(1, 1, At, B1); PG8_BAR; PG8_SCHED;
;             } else {
;             PG8_LDB(B0, 0, 0); PG8_SCHED; PG8_LDA(At, 0, 0); PG8_STAGE(PG8_SA(1, 1), a1 + hstepA, voffA);
;             PG8_WAIT_L(8); PG8_BAR; PG8_WAIT_L(0); PG8_MMA(0, 0, At, B0); PG8_BAR; PG8_SCHED;
;             PG8_LDB(B1, 0, 1); PG8_STAGE(PG8_SB(0, 0), b2, voffB);
;             PG8_BAR; PG8_WAIT_L(0); PG8_MMA(0, 1, At, B1); PG8_BAR;
;             PG8_LDA(At, 0, 1); PG8_STAGE(PG8_SA(0, 0), a2, voffA);
;             PG8_BAR; PG8_WAIT_L(0); PG8_MMA(1, 0, At, B0); PG8_BAR; PG8_SCHED;
;             PG8_STAGE(PG8_SB(0, 1), b2 + hstepB, voffB);
;             PG8_WAIT_V(6); PG8_BAR; PG8_MMA(1, 1, At, B1); PG8_BAR;
;             PG8_LDB(B0, 1, 0); PG8_SCHED; PG8_LDA(At, 1, 0); PG8_STAGE(PG8_SA(0, 1), a2 + hstepA, voffA);
;             PG8_WAIT_L(8); PG8_BAR; PG8_WAIT_L(0); PG8_MMA(0, 0, At, B0); PG8_BAR; PG8_SCHED;
;             PG8_LDB(B1, 1, 1); PG8_STAGE(PG8_SB(1, 0), b3, voffB);
;             PG8_BAR; PG8_WAIT_L(0); PG8_MMA(0, 1, At, B1); PG8_BAR;
;             PG8_LDA(At, 1, 1); PG8_STAGE(PG8_SA(1, 0), a3, voffA);
;             PG8_BAR; PG8_WAIT_L(0); PG8_MMA(1, 0, At, B0); PG8_BAR; PG8_SCHED;
;             PG8_STAGE(PG8_SB(1, 1), b3 + hstepB, voffB);
;             PG8_WAIT_V(6); PG8_BAR; PG8_MMA(1, 1, At, B1); PG8_BAR;
;             }
;         }
;         if constexpr (ALIGN_EPI) { if (wr == 0) PG8_BAR; }
;         if constexpr (Epi::FUSED_LAST) { if (has_next) E(acc, cur, wr, wc, fr, fq); }
;         else E(acc, cur, wr, wc, fr, fq);
;         if (!has_next) break;
	s_mov_b32 m0, s72
	v_lshl_add_u64 v[138:139], v[138:139], 0, s[14:15]
	ds_read_b128 v[174:177], v140 offset:49152
	ds_read_b128 v[178:181], v140 offset:50176
	ds_read_b128 v[182:185], v140 offset:51200
	ds_read_b128 v[186:189], v140 offset:52224
	ds_read_b128 v[190:193], v140 offset:53248
	ds_read_b128 v[194:197], v140 offset:54272
	ds_read_b128 v[198:201], v140 offset:55296
	ds_read_b128 v[214:217], v140 offset:56320
	global_load_lds_dwordx4 v[138:139], off
	v_lshl_add_u64 v[138:139], v[218:219], 0, s[14:15]
	s_mov_b32 m0, s59
	s_nop 0
	global_load_lds_dwordx4 v[138:139], off
	v_lshl_add_u64 v[138:139], s[26:27], 0, v[202:203]
	s_mov_b32 m0, s95
	s_nop 0
	global_load_lds_dwordx4 v[138:139], off
	v_lshl_add_u64 v[138:139], s[26:27], 0, v[134:135]
	s_mov_b32 m0, s94
	s_nop 0
	global_load_lds_dwordx4 v[138:139], off
	v_lshl_add_u64 v[138:139], v[220:221], 0, s[14:15]
	s_mov_b32 m0, s63
	s_nop 0
	global_load_lds_dwordx4 v[138:139], off
	v_lshl_add_u64 v[138:139], v[222:223], 0, s[14:15]
	s_mov_b32 m0, s64
	s_nop 0
	global_load_lds_dwordx4 v[138:139], off
	s_waitcnt vmcnt(8)
	s_waitcnt lgkmcnt(0)
	s_barrier
	s_waitcnt lgkmcnt(0)
	v_mfma_f32_16x16x32_bf16 v[62:65], v[142:145], v[174:177], v[62:65]
	v_mfma_f32_16x16x32_bf16 v[58:61], v[150:153], v[174:177], v[58:61]
	v_mfma_f32_16x16x32_bf16 v[54:57], v[142:145], v[182:185], v[54:57]
	v_mfma_f32_16x16x32_bf16 v[50:53], v[150:153], v[182:185], v[50:53]
	v_mfma_f32_16x16x32_bf16 v[46:49], v[142:145], v[190:193], v[46:49]
	v_mfma_f32_16x16x32_bf16 v[42:45], v[150:153], v[190:193], v[42:45]
	v_mfma_f32_16x16x32_bf16 v[38:41], v[142:145], v[198:201], v[38:41]
	v_mfma_f32_16x16x32_bf16 v[34:37], v[150:153], v[198:201], v[34:37]
	v_mfma_f32_16x16x32_bf16 v[62:65], v[146:149], v[178:181], v[62:65]
	v_mfma_f32_16x16x32_bf16 v[58:61], v[154:157], v[178:181], v[58:61]
	v_mfma_f32_16x16x32_bf16 v[54:57], v[146:149], v[186:189], v[54:57]
	v_mfma_f32_16x16x32_bf16 v[50:53], v[154:157], v[186:189], v[50:53]
	v_mfma_f32_16x16x32_bf16 v[46:49], v[146:149], v[194:197], v[46:49]
	v_mfma_f32_16x16x32_bf16 v[42:45], v[154:157], v[194:197], v[42:45]
	v_mfma_f32_16x16x32_bf16 v[38:41], v[146:149], v[214:217], v[38:41]
	v_mfma_f32_16x16x32_bf16 v[34:37], v[154:157], v[214:217], v[34:37]
	v_mfma_f32_16x16x32_bf16 v[30:33], v[158:161], v[174:177], v[30:33]
	v_mfma_f32_16x16x32_bf16 v[26:29], v[166:169], v[174:177], v[26:29]
	v_mfma_f32_16x16x32_bf16 v[22:25], v[158:161], v[182:185], v[22:25]
	v_mfma_f32_16x16x32_bf16 v[18:21], v[166:169], v[182:185], v[18:21]
	v_mfma_f32_16x16x32_bf16 v[14:17], v[158:161], v[190:193], v[14:17]
	v_mfma_f32_16x16x32_bf16 v[10:13], v[166:169], v[190:193], v[10:13]
	v_mfma_f32_16x16x32_bf16 v[6:9], v[158:161], v[198:201], v[6:9]
	v_mfma_f32_16x16x32_bf16 v[2:5], v[166:169], v[198:201], v[2:5]
	v_mfma_f32_16x16x32_bf16 v[30:33], v[162:165], v[178:181], v[30:33]
	v_mfma_f32_16x16x32_bf16 v[26:29], v[170:173], v[178:181], v[26:29]
	v_mfma_f32_16x16x32_bf16 v[22:25], v[162:165], v[186:189], v[22:25]
	v_mfma_f32_16x16x32_bf16 v[18:21], v[170:173], v[186:189], v[18:21]
	v_mfma_f32_16x16x32_bf16 v[14:17], v[162:165], v[194:197], v[14:17]
	v_mfma_f32_16x16x32_bf16 v[10:13], v[170:173], v[194:197], v[10:13]
	v_mfma_f32_16x16x32_bf16 v[6:9], v[162:165], v[214:217], v[6:9]
	v_mfma_f32_16x16x32_bf16 v[2:5], v[170:173], v[214:217], v[2:5]
	s_barrier
	s_andn2_b64 vcc, exec, s[24:25]
	s_mov_b64 s[26:27], -1
	s_mov_b64 s[24:25], 0
	s_mov_b64 s[34:35], 0x100
	s_cbranch_vccz .LBB0_748
	s_and_b64 vcc, s[6:7], s[40:41]
	s_cbranch_vccz .LBB0_751
	s_barrier
